# rw_post loop software pipelined, DPP sums instead of bpermute
# speedup vs baseline: 1.0387x; 1.0007x over previous
.LBB0_2167:
	v_readlane_b32 s0, v251, 24
	s_cmpk_gt_i32 s88, 0x7fff
	v_readlane_b32 s8, v251, 32
	v_readlane_b32 s9, v251, 33
	v_readlane_b32 s10, v251, 34
	v_readlane_b32 s11, v251, 35
	v_readlane_b32 s12, v251, 36
	v_readlane_b32 s13, v251, 37
	v_readlane_b32 s1, v251, 25
	v_readlane_b32 s2, v251, 26
	v_readlane_b32 s3, v251, 27
	v_readlane_b32 s4, v251, 28
	v_readlane_b32 s5, v251, 29
	v_readlane_b32 s6, v251, 30
	v_readlane_b32 s7, v251, 31
	v_readlane_b32 s14, v251, 38
	v_readlane_b32 s15, v251, 39
	s_cbranch_scc1 .LBB0_2170
	v_lshlrev_b32_e32 v0, 5, v152
	v_mov_b32_e32 v1, 0
	v_lshl_add_u64 v[2:3], s[8:9], 0, v[0:1]
	v_lshl_add_u64 v[4:5], s[10:11], 0, v[0:1]
	v_lshl_add_u64 v[6:7], s[12:13], 0, v[0:1]
	v_mbcnt_hi_u32_b32 v0, -1, v155
	v_and_b32_e32 v9, 64, v0
	s_ashr_i32 s89, s88, 31
	v_xor_b32_e32 v8, 1, v0
	v_add_u32_e32 v10, 64, v9
	s_lshl_b64 s[4:5], s[88:89], 10
	v_cmp_lt_i32_e32 vcc, v8, v10
	v_xor_b32_e32 v9, 2, v0
	s_add_u32 s0, s96, s4
	v_cndmask_b32_e32 v8, v0, v8, vcc
	v_cmp_lt_i32_e32 vcc, v9, v10
	v_xor_b32_e32 v11, 4, v0
	s_addc_u32 s1, s97, s5
	s_ashr_i32 s95, s94, 31
	v_cndmask_b32_e32 v9, v0, v9, vcc
	v_cmp_lt_i32_e32 vcc, v11, v10
	s_lshl_b64 s[2:3], s[94:95], 10
	s_add_u32 s4, s74, s4
	v_cndmask_b32_e32 v0, v0, v11, vcc
	v_lshlrev_b32_e32 v8, 2, v8
	v_lshlrev_b32_e32 v9, 2, v9
	v_lshlrev_b32_e32 v10, 2, v0
	v_lshlrev_b32_e32 v0, 4, v152
	s_addc_u32 s5, s75, s5
	s_brev_b32 s6, 32
	s_mov_b32 s7, 0x6000000
	s_mov_b32 s8, 0x1dd00000
	v_mov_b32_e32 v11, 0x3a27c5ac
	s_mov_b32 s9, 0x800000
	s_mov_b32 s10, s88
	global_load_dwordx4 v[56:59], v[2:3], off
	global_load_dwordx4 v[60:63], v[2:3], off offset:16
	global_load_dwordx4 v[64:67], v[4:5], off
	global_load_dwordx4 v[68:71], v[4:5], off offset:16
	global_load_dwordx4 v[72:75], v[6:7], off
	global_load_dwordx4 v[76:79], v[6:7], off offset:16
	s_add_u32 s76, s4, s6
	s_addc_u32 s77, s5, 0
	s_add_u32 s78, s4, s7
	s_addc_u32 s79, s5, 0
	s_add_u32 s80, s0, 0x7000000
	s_addc_u32 s81, s1, 0
	s_add_u32 s82, s0, s8
	s_addc_u32 s83, s1, 0
	s_mov_b32 s32, s10
	global_load_dwordx4 v[80:83], v0, s[4:5]
	global_load_dwordx4 v[84:87], v0, s[80:81]
	global_load_dwordx4 v[88:91], v0, s[76:77]
	global_load_dwordx4 v[92:95], v0, s[78:79]
	global_load_dwordx4 v[96:99], v0, s[82:83]
	v_lshl_add_u64 v[100:101], s[80:81], 0, v[0:1]
	s_add_i32 s32, s32, s94
	s_cmp_lt_i32 s32, 0x8000
	s_cselect_b32 s85, s2, 0
	s_cselect_b32 s91, s3, 0
	s_add_u32 s4, s4, s85
	s_addc_u32 s5, s5, s91
	s_add_u32 s76, s76, s85
	s_addc_u32 s77, s77, s91
	s_add_u32 s78, s78, s85
	s_addc_u32 s79, s79, s91
	s_add_u32 s80, s80, s85
	s_addc_u32 s81, s81, s91
	s_add_u32 s82, s82, s85
	s_addc_u32 s83, s83, s91
	global_load_dwordx4 v[104:107], v0, s[4:5]
	global_load_dwordx4 v[108:111], v0, s[80:81]
	global_load_dwordx4 v[112:115], v0, s[76:77]
	global_load_dwordx4 v[116:119], v0, s[78:79]
	global_load_dwordx4 v[120:123], v0, s[82:83]
	v_lshl_add_u64 v[124:125], s[80:81], 0, v[0:1]
	s_add_i32 s32, s32, s94
	s_cmp_lt_i32 s32, 0x8000
	s_cselect_b32 s85, s2, 0
	s_cselect_b32 s91, s3, 0
	s_add_u32 s4, s4, s85
	s_addc_u32 s5, s5, s91
	s_add_u32 s76, s76, s85
	s_addc_u32 s77, s77, s91
	s_add_u32 s78, s78, s85
	s_addc_u32 s79, s79, s91
	s_add_u32 s80, s80, s85
	s_addc_u32 s81, s81, s91
	s_add_u32 s82, s82, s85
	s_addc_u32 s83, s83, s91
	global_load_dwordx4 v[128:131], v0, s[4:5]
	global_load_dwordx4 v[132:135], v0, s[80:81]
	global_load_dwordx4 v[136:139], v0, s[76:77]
	global_load_dwordx4 v[140:143], v0, s[78:79]
	global_load_dwordx4 v[144:147], v0, s[82:83]
	v_lshl_add_u64 v[148:149], s[80:81], 0, v[0:1]
	s_add_i32 s32, s32, s94
	s_cmp_lt_i32 s32, 0x8000
	s_cselect_b32 s85, s2, 0
	s_cselect_b32 s91, s3, 0
	s_add_u32 s4, s4, s85
	s_addc_u32 s5, s5, s91
	s_add_u32 s76, s76, s85
	s_addc_u32 s77, s77, s91
	s_add_u32 s78, s78, s85
	s_addc_u32 s79, s79, s91
	s_add_u32 s80, s80, s85
	s_addc_u32 s81, s81, s91
	s_add_u32 s82, s82, s85
	s_addc_u32 s83, s83, s91
	s_waitcnt vmcnt(10)
	v_lshlrev_b32_e32 v160, 16, v84
	v_and_b32_e32 v161, 0xffff0000, v84
	v_lshlrev_b32_e32 v162, 16, v85
	v_and_b32_e32 v163, 0xffff0000, v85
	v_lshlrev_b32_e32 v164, 16, v86
	v_and_b32_e32 v165, 0xffff0000, v86
	v_lshlrev_b32_e32 v166, 16, v87
	v_and_b32_e32 v167, 0xffff0000, v87
	v_lshlrev_b32_e32 v168, 16, v80
	v_and_b32_e32 v169, 0xffff0000, v80
	v_lshlrev_b32_e32 v170, 16, v81
	v_and_b32_e32 v171, 0xffff0000, v81
	v_lshlrev_b32_e32 v172, 16, v82
	v_and_b32_e32 v173, 0xffff0000, v82
	v_lshlrev_b32_e32 v174, 16, v83
	v_and_b32_e32 v175, 0xffff0000, v83
	v_lshlrev_b32_e32 v176, 16, v88
	v_and_b32_e32 v177, 0xffff0000, v88
	v_lshlrev_b32_e32 v178, 16, v89
	v_and_b32_e32 v179, 0xffff0000, v89
	v_lshlrev_b32_e32 v180, 16, v90
	v_and_b32_e32 v181, 0xffff0000, v90
	v_lshlrev_b32_e32 v182, 16, v91
	v_and_b32_e32 v183, 0xffff0000, v91
	v_add_f32_e32 v192, 0, v160
	v_pk_mul_f32 v[184:185], v[168:169], v[176:177]
	v_pk_mul_f32 v[186:187], v[170:171], v[178:179]
	v_pk_mul_f32 v[188:189], v[172:173], v[180:181]
	v_pk_mul_f32 v[190:191], v[174:175], v[182:183]
	v_add_f32_e32 v192, v192, v161
	v_pk_mul_f32 v[184:185], v[184:185], v[56:57]
	v_add_f32_e32 v192, v192, v162
	v_pk_mul_f32 v[186:187], v[186:187], v[58:59]
	v_add_f32_e32 v192, v192, v163
	v_pk_mul_f32 v[188:189], v[188:189], v[60:61]
	v_add_f32_e32 v192, v192, v164
	v_pk_mul_f32 v[190:191], v[190:191], v[62:63]
	v_add_f32_e32 v192, v192, v165
	v_add_f32_e32 v192, v192, v166
	v_add_f32_e32 v192, v192, v167
	v_add_f32_e32 v196, 0, v184
	v_add_f32_e32 v196, v185, v196
	v_add_f32_e32 v196, v186, v196
	v_add_f32_e32 v196, v187, v196
	v_add_f32_e32 v196, v188, v196
	v_add_f32_e32 v196, v189, v196
	v_add_f32_e32 v196, v190, v196
	v_add_f32_e32 v196, v191, v196
	v_lshlrev_b32_e32 v168, 16, v92
	v_and_b32_e32 v169, 0xffff0000, v92
	v_add_f32_dpp v192, v192, v192 quad_perm:[1,0,3,2] row_mask:0xf bank_mask:0xf bound_ctrl:1
	v_add_f32_dpp v196, v196, v196 quad_perm:[1,0,3,2] row_mask:0xf bank_mask:0xf bound_ctrl:1
	v_lshlrev_b32_e32 v170, 16, v93
	v_and_b32_e32 v171, 0xffff0000, v93
	v_add_f32_dpp v192, v192, v192 quad_perm:[2,3,0,1] row_mask:0xf bank_mask:0xf bound_ctrl:1
	v_add_f32_dpp v196, v196, v196 quad_perm:[2,3,0,1] row_mask:0xf bank_mask:0xf bound_ctrl:1
	v_lshlrev_b32_e32 v172, 16, v94
	v_and_b32_e32 v173, 0xffff0000, v94
	v_add_f32_dpp v192, v192, v192 row_half_mirror row_mask:0xf bank_mask:0xf bound_ctrl:1
	v_add_f32_dpp v196, v196, v196 row_half_mirror row_mask:0xf bank_mask:0xf bound_ctrl:1
	v_lshlrev_b32_e32 v174, 16, v95
	v_and_b32_e32 v175, 0xffff0000, v95
	v_mul_f32_e32 v194, 0x3c800000, v192
	v_pk_add_f32 v[204:205], v[160:161], v[194:195] op_sel_hi:[1,0] neg_lo:[0,1] neg_hi:[0,1]
	v_pk_add_f32 v[206:207], v[162:163], v[194:195] op_sel_hi:[1,0] neg_lo:[0,1] neg_hi:[0,1]
	v_pk_add_f32 v[208:209], v[164:165], v[194:195] op_sel_hi:[1,0] neg_lo:[0,1] neg_hi:[0,1]
	v_pk_add_f32 v[210:211], v[166:167], v[194:195] op_sel_hi:[1,0] neg_lo:[0,1] neg_hi:[0,1]
	v_pk_mul_f32 v[184:185], v[204:205], v[204:205]
	v_pk_mul_f32 v[186:187], v[206:207], v[206:207]
	v_pk_mul_f32 v[188:189], v[208:209], v[208:209]
	v_pk_mul_f32 v[190:191], v[210:211], v[210:211]
	v_add_f32_e32 v198, v184, v185
	v_add_f32_e32 v198, v186, v198
	v_add_f32_e32 v198, v187, v198
	v_add_f32_e32 v198, v188, v198
	v_add_f32_e32 v198, v189, v198
	v_add_f32_e32 v198, v190, v198
	v_add_f32_e32 v198, v191, v198
	v_lshlrev_b32_e32 v176, 16, v96
	v_and_b32_e32 v177, 0xffff0000, v96
	v_add_f32_dpp v198, v198, v198 quad_perm:[1,0,3,2] row_mask:0xf bank_mask:0xf bound_ctrl:1
	v_lshlrev_b32_e32 v178, 16, v97
	v_and_b32_e32 v179, 0xffff0000, v97
	v_add_f32_dpp v198, v198, v198 quad_perm:[2,3,0,1] row_mask:0xf bank_mask:0xf bound_ctrl:1
	v_lshlrev_b32_e32 v180, 16, v98
	v_and_b32_e32 v181, 0xffff0000, v98
	v_add_f32_dpp v198, v198, v198 row_half_mirror row_mask:0xf bank_mask:0xf bound_ctrl:1
	v_lshlrev_b32_e32 v182, 16, v99
	v_and_b32_e32 v183, 0xffff0000, v99
	v_fmamk_f32 v198, v198, 0x3c800000, v11
	v_mul_f32_e32 v199, 0x4b800000, v198
	v_cmp_gt_f32_e32 vcc, s9, v198
	s_nop 1
	v_cndmask_b32_e32 v198, v198, v199, vcc
	v_rsq_f32_e32 v198, v198
	s_nop 0
	v_mul_f32_e32 v200, 0x45800000, v198
	v_cndmask_b32_e32 v200, v198, v200, vcc
	v_pk_mul_f32 v[204:205], v[204:205], v[200:201] op_sel_hi:[1,0]
	v_pk_mul_f32 v[206:207], v[206:207], v[200:201] op_sel_hi:[1,0]
	v_pk_mul_f32 v[208:209], v[208:209], v[200:201] op_sel_hi:[1,0]
	v_pk_mul_f32 v[210:211], v[210:211], v[200:201] op_sel_hi:[1,0]
	v_pk_fma_f32 v[204:205], v[64:65], v[204:205], v[72:73]
	v_pk_fma_f32 v[206:207], v[66:67], v[206:207], v[74:75]
	v_pk_fma_f32 v[208:209], v[68:69], v[208:209], v[76:77]
	v_pk_fma_f32 v[210:211], v[70:71], v[210:211], v[78:79]
	v_pk_fma_f32 v[204:205], v[196:197], v[168:169], v[204:205] op_sel_hi:[0,1,1]
	v_pk_fma_f32 v[206:207], v[196:197], v[170:171], v[206:207] op_sel_hi:[0,1,1]
	v_pk_fma_f32 v[208:209], v[196:197], v[172:173], v[208:209] op_sel_hi:[0,1,1]
	v_pk_fma_f32 v[210:211], v[196:197], v[174:175], v[210:211] op_sel_hi:[0,1,1]
	v_pk_mul_f32 v[204:205], v[204:205], v[176:177]
	v_pk_mul_f32 v[206:207], v[206:207], v[178:179]
	v_pk_mul_f32 v[208:209], v[208:209], v[180:181]
	v_pk_mul_f32 v[210:211], v[210:211], v[182:183]
	v_cvt_pk_bf16_f32 v212, v204, v205
	v_cvt_pk_bf16_f32 v213, v206, v207
	v_cvt_pk_bf16_f32 v214, v208, v209
	v_cvt_pk_bf16_f32 v215, v210, v211
	global_store_dwordx4 v[100:101], v[212:215], off
	s_add_i32 s10, s10, s94
	s_cmp_lt_i32 s10, 0x8000
	s_cbranch_scc0 .Lrwp_done
.Lrwp_loop:
	global_load_dwordx4 v[80:83], v0, s[4:5]
	global_load_dwordx4 v[84:87], v0, s[80:81]
	global_load_dwordx4 v[88:91], v0, s[76:77]
	global_load_dwordx4 v[92:95], v0, s[78:79]
	global_load_dwordx4 v[96:99], v0, s[82:83]
	v_lshl_add_u64 v[100:101], s[80:81], 0, v[0:1]
	s_add_i32 s32, s32, s94
	s_cmp_lt_i32 s32, 0x8000
	s_cselect_b32 s85, s2, 0
	s_cselect_b32 s91, s3, 0
	s_add_u32 s4, s4, s85
	s_addc_u32 s5, s5, s91
	s_add_u32 s76, s76, s85
	s_addc_u32 s77, s77, s91
	s_add_u32 s78, s78, s85
	s_addc_u32 s79, s79, s91
	s_add_u32 s80, s80, s85
	s_addc_u32 s81, s81, s91
	s_add_u32 s82, s82, s85
	s_addc_u32 s83, s83, s91
	s_waitcnt vmcnt(11)
	v_lshlrev_b32_e32 v160, 16, v108
	v_and_b32_e32 v161, 0xffff0000, v108
	v_lshlrev_b32_e32 v162, 16, v109
	v_and_b32_e32 v163, 0xffff0000, v109
	v_lshlrev_b32_e32 v164, 16, v110
	v_and_b32_e32 v165, 0xffff0000, v110
	v_lshlrev_b32_e32 v166, 16, v111
	v_and_b32_e32 v167, 0xffff0000, v111
	v_lshlrev_b32_e32 v168, 16, v104
	v_and_b32_e32 v169, 0xffff0000, v104
	v_lshlrev_b32_e32 v170, 16, v105
	v_and_b32_e32 v171, 0xffff0000, v105
	v_lshlrev_b32_e32 v172, 16, v106
	v_and_b32_e32 v173, 0xffff0000, v106
	v_lshlrev_b32_e32 v174, 16, v107
	v_and_b32_e32 v175, 0xffff0000, v107
	v_lshlrev_b32_e32 v176, 16, v112
	v_and_b32_e32 v177, 0xffff0000, v112
	v_lshlrev_b32_e32 v178, 16, v113
	v_and_b32_e32 v179, 0xffff0000, v113
	v_lshlrev_b32_e32 v180, 16, v114
	v_and_b32_e32 v181, 0xffff0000, v114
	v_lshlrev_b32_e32 v182, 16, v115
	v_and_b32_e32 v183, 0xffff0000, v115
	v_add_f32_e32 v192, 0, v160
	v_pk_mul_f32 v[184:185], v[168:169], v[176:177]
	v_pk_mul_f32 v[186:187], v[170:171], v[178:179]
	v_pk_mul_f32 v[188:189], v[172:173], v[180:181]
	v_pk_mul_f32 v[190:191], v[174:175], v[182:183]
	v_add_f32_e32 v192, v192, v161
	v_pk_mul_f32 v[184:185], v[184:185], v[56:57]
	v_add_f32_e32 v192, v192, v162
	v_pk_mul_f32 v[186:187], v[186:187], v[58:59]
	v_add_f32_e32 v192, v192, v163
	v_pk_mul_f32 v[188:189], v[188:189], v[60:61]
	v_add_f32_e32 v192, v192, v164
	v_pk_mul_f32 v[190:191], v[190:191], v[62:63]
	v_add_f32_e32 v192, v192, v165
	v_add_f32_e32 v192, v192, v166
	v_add_f32_e32 v192, v192, v167
	v_add_f32_e32 v196, 0, v184
	v_add_f32_e32 v196, v185, v196
	v_add_f32_e32 v196, v186, v196
	v_add_f32_e32 v196, v187, v196
	v_add_f32_e32 v196, v188, v196
	v_add_f32_e32 v196, v189, v196
	v_add_f32_e32 v196, v190, v196
	v_add_f32_e32 v196, v191, v196
	v_lshlrev_b32_e32 v168, 16, v116
	v_and_b32_e32 v169, 0xffff0000, v116
	v_add_f32_dpp v192, v192, v192 quad_perm:[1,0,3,2] row_mask:0xf bank_mask:0xf bound_ctrl:1
	v_add_f32_dpp v196, v196, v196 quad_perm:[1,0,3,2] row_mask:0xf bank_mask:0xf bound_ctrl:1
	v_lshlrev_b32_e32 v170, 16, v117
	v_and_b32_e32 v171, 0xffff0000, v117
	v_add_f32_dpp v192, v192, v192 quad_perm:[2,3,0,1] row_mask:0xf bank_mask:0xf bound_ctrl:1
	v_add_f32_dpp v196, v196, v196 quad_perm:[2,3,0,1] row_mask:0xf bank_mask:0xf bound_ctrl:1
	v_lshlrev_b32_e32 v172, 16, v118
	v_and_b32_e32 v173, 0xffff0000, v118
	v_add_f32_dpp v192, v192, v192 row_half_mirror row_mask:0xf bank_mask:0xf bound_ctrl:1
	v_add_f32_dpp v196, v196, v196 row_half_mirror row_mask:0xf bank_mask:0xf bound_ctrl:1
	v_lshlrev_b32_e32 v174, 16, v119
	v_and_b32_e32 v175, 0xffff0000, v119
	v_mul_f32_e32 v194, 0x3c800000, v192
	v_pk_add_f32 v[204:205], v[160:161], v[194:195] op_sel_hi:[1,0] neg_lo:[0,1] neg_hi:[0,1]
	v_pk_add_f32 v[206:207], v[162:163], v[194:195] op_sel_hi:[1,0] neg_lo:[0,1] neg_hi:[0,1]
	v_pk_add_f32 v[208:209], v[164:165], v[194:195] op_sel_hi:[1,0] neg_lo:[0,1] neg_hi:[0,1]
	v_pk_add_f32 v[210:211], v[166:167], v[194:195] op_sel_hi:[1,0] neg_lo:[0,1] neg_hi:[0,1]
	v_pk_mul_f32 v[184:185], v[204:205], v[204:205]
	v_pk_mul_f32 v[186:187], v[206:207], v[206:207]
	v_pk_mul_f32 v[188:189], v[208:209], v[208:209]
	v_pk_mul_f32 v[190:191], v[210:211], v[210:211]
	v_add_f32_e32 v198, v184, v185
	v_add_f32_e32 v198, v186, v198
	v_add_f32_e32 v198, v187, v198
	v_add_f32_e32 v198, v188, v198
	v_add_f32_e32 v198, v189, v198
	v_add_f32_e32 v198, v190, v198
	v_add_f32_e32 v198, v191, v198
	v_lshlrev_b32_e32 v176, 16, v120
	v_and_b32_e32 v177, 0xffff0000, v120
	v_add_f32_dpp v198, v198, v198 quad_perm:[1,0,3,2] row_mask:0xf bank_mask:0xf bound_ctrl:1
	v_lshlrev_b32_e32 v178, 16, v121
	v_and_b32_e32 v179, 0xffff0000, v121
	v_add_f32_dpp v198, v198, v198 quad_perm:[2,3,0,1] row_mask:0xf bank_mask:0xf bound_ctrl:1
	v_lshlrev_b32_e32 v180, 16, v122
	v_and_b32_e32 v181, 0xffff0000, v122
	v_add_f32_dpp v198, v198, v198 row_half_mirror row_mask:0xf bank_mask:0xf bound_ctrl:1
	v_lshlrev_b32_e32 v182, 16, v123
	v_and_b32_e32 v183, 0xffff0000, v123
	v_fmamk_f32 v198, v198, 0x3c800000, v11
	v_mul_f32_e32 v199, 0x4b800000, v198
	v_cmp_gt_f32_e32 vcc, s9, v198
	s_nop 1
	v_cndmask_b32_e32 v198, v198, v199, vcc
	v_rsq_f32_e32 v198, v198
	s_nop 0
	v_mul_f32_e32 v200, 0x45800000, v198
	v_cndmask_b32_e32 v200, v198, v200, vcc
	v_pk_mul_f32 v[204:205], v[204:205], v[200:201] op_sel_hi:[1,0]
	v_pk_mul_f32 v[206:207], v[206:207], v[200:201] op_sel_hi:[1,0]
	v_pk_mul_f32 v[208:209], v[208:209], v[200:201] op_sel_hi:[1,0]
	v_pk_mul_f32 v[210:211], v[210:211], v[200:201] op_sel_hi:[1,0]
	v_pk_fma_f32 v[204:205], v[64:65], v[204:205], v[72:73]
	v_pk_fma_f32 v[206:207], v[66:67], v[206:207], v[74:75]
	v_pk_fma_f32 v[208:209], v[68:69], v[208:209], v[76:77]
	v_pk_fma_f32 v[210:211], v[70:71], v[210:211], v[78:79]
	v_pk_fma_f32 v[204:205], v[196:197], v[168:169], v[204:205] op_sel_hi:[0,1,1]
	v_pk_fma_f32 v[206:207], v[196:197], v[170:171], v[206:207] op_sel_hi:[0,1,1]
	v_pk_fma_f32 v[208:209], v[196:197], v[172:173], v[208:209] op_sel_hi:[0,1,1]
	v_pk_fma_f32 v[210:211], v[196:197], v[174:175], v[210:211] op_sel_hi:[0,1,1]
	v_pk_mul_f32 v[204:205], v[204:205], v[176:177]
	v_pk_mul_f32 v[206:207], v[206:207], v[178:179]
	v_pk_mul_f32 v[208:209], v[208:209], v[180:181]
	v_pk_mul_f32 v[210:211], v[210:211], v[182:183]
	v_cvt_pk_bf16_f32 v212, v204, v205
	v_cvt_pk_bf16_f32 v213, v206, v207
	v_cvt_pk_bf16_f32 v214, v208, v209
	v_cvt_pk_bf16_f32 v215, v210, v211
	global_store_dwordx4 v[124:125], v[212:215], off
	s_add_i32 s10, s10, s94
	s_cmp_lt_i32 s10, 0x8000
	s_cbranch_scc0 .Lrwp_done
	global_load_dwordx4 v[104:107], v0, s[4:5]
	global_load_dwordx4 v[108:111], v0, s[80:81]
	global_load_dwordx4 v[112:115], v0, s[76:77]
	global_load_dwordx4 v[116:119], v0, s[78:79]
	global_load_dwordx4 v[120:123], v0, s[82:83]
	v_lshl_add_u64 v[124:125], s[80:81], 0, v[0:1]
	s_add_i32 s32, s32, s94
	s_cmp_lt_i32 s32, 0x8000
	s_cselect_b32 s85, s2, 0
	s_cselect_b32 s91, s3, 0
	s_add_u32 s4, s4, s85
	s_addc_u32 s5, s5, s91
	s_add_u32 s76, s76, s85
	s_addc_u32 s77, s77, s91
	s_add_u32 s78, s78, s85
	s_addc_u32 s79, s79, s91
	s_add_u32 s80, s80, s85
	s_addc_u32 s81, s81, s91
	s_add_u32 s82, s82, s85
	s_addc_u32 s83, s83, s91
	s_waitcnt vmcnt(11)
	v_lshlrev_b32_e32 v160, 16, v132
	v_and_b32_e32 v161, 0xffff0000, v132
	v_lshlrev_b32_e32 v162, 16, v133
	v_and_b32_e32 v163, 0xffff0000, v133
	v_lshlrev_b32_e32 v164, 16, v134
	v_and_b32_e32 v165, 0xffff0000, v134
	v_lshlrev_b32_e32 v166, 16, v135
	v_and_b32_e32 v167, 0xffff0000, v135
	v_lshlrev_b32_e32 v168, 16, v128
	v_and_b32_e32 v169, 0xffff0000, v128
	v_lshlrev_b32_e32 v170, 16, v129
	v_and_b32_e32 v171, 0xffff0000, v129
	v_lshlrev_b32_e32 v172, 16, v130
	v_and_b32_e32 v173, 0xffff0000, v130
	v_lshlrev_b32_e32 v174, 16, v131
	v_and_b32_e32 v175, 0xffff0000, v131
	v_lshlrev_b32_e32 v176, 16, v136
	v_and_b32_e32 v177, 0xffff0000, v136
	v_lshlrev_b32_e32 v178, 16, v137
	v_and_b32_e32 v179, 0xffff0000, v137
	v_lshlrev_b32_e32 v180, 16, v138
	v_and_b32_e32 v181, 0xffff0000, v138
	v_lshlrev_b32_e32 v182, 16, v139
	v_and_b32_e32 v183, 0xffff0000, v139
	v_add_f32_e32 v192, 0, v160
	v_pk_mul_f32 v[184:185], v[168:169], v[176:177]
	v_pk_mul_f32 v[186:187], v[170:171], v[178:179]
	v_pk_mul_f32 v[188:189], v[172:173], v[180:181]
	v_pk_mul_f32 v[190:191], v[174:175], v[182:183]
	v_add_f32_e32 v192, v192, v161
	v_pk_mul_f32 v[184:185], v[184:185], v[56:57]
	v_add_f32_e32 v192, v192, v162
	v_pk_mul_f32 v[186:187], v[186:187], v[58:59]
	v_add_f32_e32 v192, v192, v163
	v_pk_mul_f32 v[188:189], v[188:189], v[60:61]
	v_add_f32_e32 v192, v192, v164
	v_pk_mul_f32 v[190:191], v[190:191], v[62:63]
	v_add_f32_e32 v192, v192, v165
	v_add_f32_e32 v192, v192, v166
	v_add_f32_e32 v192, v192, v167
	v_add_f32_e32 v196, 0, v184
	v_add_f32_e32 v196, v185, v196
	v_add_f32_e32 v196, v186, v196
	v_add_f32_e32 v196, v187, v196
	v_add_f32_e32 v196, v188, v196
	v_add_f32_e32 v196, v189, v196
	v_add_f32_e32 v196, v190, v196
	v_add_f32_e32 v196, v191, v196
	v_lshlrev_b32_e32 v168, 16, v140
	v_and_b32_e32 v169, 0xffff0000, v140
	v_add_f32_dpp v192, v192, v192 quad_perm:[1,0,3,2] row_mask:0xf bank_mask:0xf bound_ctrl:1
	v_add_f32_dpp v196, v196, v196 quad_perm:[1,0,3,2] row_mask:0xf bank_mask:0xf bound_ctrl:1
	v_lshlrev_b32_e32 v170, 16, v141
	v_and_b32_e32 v171, 0xffff0000, v141
	v_add_f32_dpp v192, v192, v192 quad_perm:[2,3,0,1] row_mask:0xf bank_mask:0xf bound_ctrl:1
	v_add_f32_dpp v196, v196, v196 quad_perm:[2,3,0,1] row_mask:0xf bank_mask:0xf bound_ctrl:1
	v_lshlrev_b32_e32 v172, 16, v142
	v_and_b32_e32 v173, 0xffff0000, v142
	v_add_f32_dpp v192, v192, v192 row_half_mirror row_mask:0xf bank_mask:0xf bound_ctrl:1
	v_add_f32_dpp v196, v196, v196 row_half_mirror row_mask:0xf bank_mask:0xf bound_ctrl:1
	v_lshlrev_b32_e32 v174, 16, v143
	v_and_b32_e32 v175, 0xffff0000, v143
	v_mul_f32_e32 v194, 0x3c800000, v192
	v_pk_add_f32 v[204:205], v[160:161], v[194:195] op_sel_hi:[1,0] neg_lo:[0,1] neg_hi:[0,1]
	v_pk_add_f32 v[206:207], v[162:163], v[194:195] op_sel_hi:[1,0] neg_lo:[0,1] neg_hi:[0,1]
	v_pk_add_f32 v[208:209], v[164:165], v[194:195] op_sel_hi:[1,0] neg_lo:[0,1] neg_hi:[0,1]
	v_pk_add_f32 v[210:211], v[166:167], v[194:195] op_sel_hi:[1,0] neg_lo:[0,1] neg_hi:[0,1]
	v_pk_mul_f32 v[184:185], v[204:205], v[204:205]
	v_pk_mul_f32 v[186:187], v[206:207], v[206:207]
	v_pk_mul_f32 v[188:189], v[208:209], v[208:209]
	v_pk_mul_f32 v[190:191], v[210:211], v[210:211]
	v_add_f32_e32 v198, v184, v185
	v_add_f32_e32 v198, v186, v198
	v_add_f32_e32 v198, v187, v198
	v_add_f32_e32 v198, v188, v198
	v_add_f32_e32 v198, v189, v198
	v_add_f32_e32 v198, v190, v198
	v_add_f32_e32 v198, v191, v198
	v_lshlrev_b32_e32 v176, 16, v144
	v_and_b32_e32 v177, 0xffff0000, v144
	v_add_f32_dpp v198, v198, v198 quad_perm:[1,0,3,2] row_mask:0xf bank_mask:0xf bound_ctrl:1
	v_lshlrev_b32_e32 v178, 16, v145
	v_and_b32_e32 v179, 0xffff0000, v145
	v_add_f32_dpp v198, v198, v198 quad_perm:[2,3,0,1] row_mask:0xf bank_mask:0xf bound_ctrl:1
	v_lshlrev_b32_e32 v180, 16, v146
	v_and_b32_e32 v181, 0xffff0000, v146
	v_add_f32_dpp v198, v198, v198 row_half_mirror row_mask:0xf bank_mask:0xf bound_ctrl:1
	v_lshlrev_b32_e32 v182, 16, v147
	v_and_b32_e32 v183, 0xffff0000, v147
	v_fmamk_f32 v198, v198, 0x3c800000, v11
	v_mul_f32_e32 v199, 0x4b800000, v198
	v_cmp_gt_f32_e32 vcc, s9, v198
	s_nop 1
	v_cndmask_b32_e32 v198, v198, v199, vcc
	v_rsq_f32_e32 v198, v198
	s_nop 0
	v_mul_f32_e32 v200, 0x45800000, v198
	v_cndmask_b32_e32 v200, v198, v200, vcc
	v_pk_mul_f32 v[204:205], v[204:205], v[200:201] op_sel_hi:[1,0]
	v_pk_mul_f32 v[206:207], v[206:207], v[200:201] op_sel_hi:[1,0]
	v_pk_mul_f32 v[208:209], v[208:209], v[200:201] op_sel_hi:[1,0]
	v_pk_mul_f32 v[210:211], v[210:211], v[200:201] op_sel_hi:[1,0]
	v_pk_fma_f32 v[204:205], v[64:65], v[204:205], v[72:73]
	v_pk_fma_f32 v[206:207], v[66:67], v[206:207], v[74:75]
	v_pk_fma_f32 v[208:209], v[68:69], v[208:209], v[76:77]
	v_pk_fma_f32 v[210:211], v[70:71], v[210:211], v[78:79]
	v_pk_fma_f32 v[204:205], v[196:197], v[168:169], v[204:205] op_sel_hi:[0,1,1]
	v_pk_fma_f32 v[206:207], v[196:197], v[170:171], v[206:207] op_sel_hi:[0,1,1]
	v_pk_fma_f32 v[208:209], v[196:197], v[172:173], v[208:209] op_sel_hi:[0,1,1]
	v_pk_fma_f32 v[210:211], v[196:197], v[174:175], v[210:211] op_sel_hi:[0,1,1]
	v_pk_mul_f32 v[204:205], v[204:205], v[176:177]
	v_pk_mul_f32 v[206:207], v[206:207], v[178:179]
	v_pk_mul_f32 v[208:209], v[208:209], v[180:181]
	v_pk_mul_f32 v[210:211], v[210:211], v[182:183]
	v_cvt_pk_bf16_f32 v212, v204, v205
	v_cvt_pk_bf16_f32 v213, v206, v207
	v_cvt_pk_bf16_f32 v214, v208, v209
	v_cvt_pk_bf16_f32 v215, v210, v211
	global_store_dwordx4 v[148:149], v[212:215], off
	s_add_i32 s10, s10, s94
	s_cmp_lt_i32 s10, 0x8000
	s_cbranch_scc0 .Lrwp_done
	global_load_dwordx4 v[128:131], v0, s[4:5]
	global_load_dwordx4 v[132:135], v0, s[80:81]
	global_load_dwordx4 v[136:139], v0, s[76:77]
	global_load_dwordx4 v[140:143], v0, s[78:79]
	global_load_dwordx4 v[144:147], v0, s[82:83]
	v_lshl_add_u64 v[148:149], s[80:81], 0, v[0:1]
	s_add_i32 s32, s32, s94
	s_cmp_lt_i32 s32, 0x8000
	s_cselect_b32 s85, s2, 0
	s_cselect_b32 s91, s3, 0
	s_add_u32 s4, s4, s85
	s_addc_u32 s5, s5, s91
	s_add_u32 s76, s76, s85
	s_addc_u32 s77, s77, s91
	s_add_u32 s78, s78, s85
	s_addc_u32 s79, s79, s91
	s_add_u32 s80, s80, s85
	s_addc_u32 s81, s81, s91
	s_add_u32 s82, s82, s85
	s_addc_u32 s83, s83, s91
	s_waitcnt vmcnt(11)
	v_lshlrev_b32_e32 v160, 16, v84
	v_and_b32_e32 v161, 0xffff0000, v84
	v_lshlrev_b32_e32 v162, 16, v85
	v_and_b32_e32 v163, 0xffff0000, v85
	v_lshlrev_b32_e32 v164, 16, v86
	v_and_b32_e32 v165, 0xffff0000, v86
	v_lshlrev_b32_e32 v166, 16, v87
	v_and_b32_e32 v167, 0xffff0000, v87
	v_lshlrev_b32_e32 v168, 16, v80
	v_and_b32_e32 v169, 0xffff0000, v80
	v_lshlrev_b32_e32 v170, 16, v81
	v_and_b32_e32 v171, 0xffff0000, v81
	v_lshlrev_b32_e32 v172, 16, v82
	v_and_b32_e32 v173, 0xffff0000, v82
	v_lshlrev_b32_e32 v174, 16, v83
	v_and_b32_e32 v175, 0xffff0000, v83
	v_lshlrev_b32_e32 v176, 16, v88
	v_and_b32_e32 v177, 0xffff0000, v88
	v_lshlrev_b32_e32 v178, 16, v89
	v_and_b32_e32 v179, 0xffff0000, v89
	v_lshlrev_b32_e32 v180, 16, v90
	v_and_b32_e32 v181, 0xffff0000, v90
	v_lshlrev_b32_e32 v182, 16, v91
	v_and_b32_e32 v183, 0xffff0000, v91
	v_add_f32_e32 v192, 0, v160
	v_pk_mul_f32 v[184:185], v[168:169], v[176:177]
	v_pk_mul_f32 v[186:187], v[170:171], v[178:179]
	v_pk_mul_f32 v[188:189], v[172:173], v[180:181]
	v_pk_mul_f32 v[190:191], v[174:175], v[182:183]
	v_add_f32_e32 v192, v192, v161
	v_pk_mul_f32 v[184:185], v[184:185], v[56:57]
	v_add_f32_e32 v192, v192, v162
	v_pk_mul_f32 v[186:187], v[186:187], v[58:59]
	v_add_f32_e32 v192, v192, v163
	v_pk_mul_f32 v[188:189], v[188:189], v[60:61]
	v_add_f32_e32 v192, v192, v164
	v_pk_mul_f32 v[190:191], v[190:191], v[62:63]
	v_add_f32_e32 v192, v192, v165
	v_add_f32_e32 v192, v192, v166
	v_add_f32_e32 v192, v192, v167
	v_add_f32_e32 v196, 0, v184
	v_add_f32_e32 v196, v185, v196
	v_add_f32_e32 v196, v186, v196
	v_add_f32_e32 v196, v187, v196
	v_add_f32_e32 v196, v188, v196
	v_add_f32_e32 v196, v189, v196
	v_add_f32_e32 v196, v190, v196
	v_add_f32_e32 v196, v191, v196
	v_lshlrev_b32_e32 v168, 16, v92
	v_and_b32_e32 v169, 0xffff0000, v92
	v_add_f32_dpp v192, v192, v192 quad_perm:[1,0,3,2] row_mask:0xf bank_mask:0xf bound_ctrl:1
	v_add_f32_dpp v196, v196, v196 quad_perm:[1,0,3,2] row_mask:0xf bank_mask:0xf bound_ctrl:1
	v_lshlrev_b32_e32 v170, 16, v93
	v_and_b32_e32 v171, 0xffff0000, v93
	v_add_f32_dpp v192, v192, v192 quad_perm:[2,3,0,1] row_mask:0xf bank_mask:0xf bound_ctrl:1
	v_add_f32_dpp v196, v196, v196 quad_perm:[2,3,0,1] row_mask:0xf bank_mask:0xf bound_ctrl:1
	v_lshlrev_b32_e32 v172, 16, v94
	v_and_b32_e32 v173, 0xffff0000, v94
	v_add_f32_dpp v192, v192, v192 row_half_mirror row_mask:0xf bank_mask:0xf bound_ctrl:1
	v_add_f32_dpp v196, v196, v196 row_half_mirror row_mask:0xf bank_mask:0xf bound_ctrl:1
	v_lshlrev_b32_e32 v174, 16, v95
	v_and_b32_e32 v175, 0xffff0000, v95
	v_mul_f32_e32 v194, 0x3c800000, v192
	v_pk_add_f32 v[204:205], v[160:161], v[194:195] op_sel_hi:[1,0] neg_lo:[0,1] neg_hi:[0,1]
	v_pk_add_f32 v[206:207], v[162:163], v[194:195] op_sel_hi:[1,0] neg_lo:[0,1] neg_hi:[0,1]
	v_pk_add_f32 v[208:209], v[164:165], v[194:195] op_sel_hi:[1,0] neg_lo:[0,1] neg_hi:[0,1]
	v_pk_add_f32 v[210:211], v[166:167], v[194:195] op_sel_hi:[1,0] neg_lo:[0,1] neg_hi:[0,1]
	v_pk_mul_f32 v[184:185], v[204:205], v[204:205]
	v_pk_mul_f32 v[186:187], v[206:207], v[206:207]
	v_pk_mul_f32 v[188:189], v[208:209], v[208:209]
	v_pk_mul_f32 v[190:191], v[210:211], v[210:211]
	v_add_f32_e32 v198, v184, v185
	v_add_f32_e32 v198, v186, v198
	v_add_f32_e32 v198, v187, v198
	v_add_f32_e32 v198, v188, v198
	v_add_f32_e32 v198, v189, v198
	v_add_f32_e32 v198, v190, v198
	v_add_f32_e32 v198, v191, v198
	v_lshlrev_b32_e32 v176, 16, v96
	v_and_b32_e32 v177, 0xffff0000, v96
	v_add_f32_dpp v198, v198, v198 quad_perm:[1,0,3,2] row_mask:0xf bank_mask:0xf bound_ctrl:1
	v_lshlrev_b32_e32 v178, 16, v97
	v_and_b32_e32 v179, 0xffff0000, v97
	v_add_f32_dpp v198, v198, v198 quad_perm:[2,3,0,1] row_mask:0xf bank_mask:0xf bound_ctrl:1
	v_lshlrev_b32_e32 v180, 16, v98
	v_and_b32_e32 v181, 0xffff0000, v98
	v_add_f32_dpp v198, v198, v198 row_half_mirror row_mask:0xf bank_mask:0xf bound_ctrl:1
	v_lshlrev_b32_e32 v182, 16, v99
	v_and_b32_e32 v183, 0xffff0000, v99
	v_fmamk_f32 v198, v198, 0x3c800000, v11
	v_mul_f32_e32 v199, 0x4b800000, v198
	v_cmp_gt_f32_e32 vcc, s9, v198
	s_nop 1
	v_cndmask_b32_e32 v198, v198, v199, vcc
	v_rsq_f32_e32 v198, v198
	s_nop 0
	v_mul_f32_e32 v200, 0x45800000, v198
	v_cndmask_b32_e32 v200, v198, v200, vcc
	v_pk_mul_f32 v[204:205], v[204:205], v[200:201] op_sel_hi:[1,0]
	v_pk_mul_f32 v[206:207], v[206:207], v[200:201] op_sel_hi:[1,0]
	v_pk_mul_f32 v[208:209], v[208:209], v[200:201] op_sel_hi:[1,0]
	v_pk_mul_f32 v[210:211], v[210:211], v[200:201] op_sel_hi:[1,0]
	v_pk_fma_f32 v[204:205], v[64:65], v[204:205], v[72:73]
	v_pk_fma_f32 v[206:207], v[66:67], v[206:207], v[74:75]
	v_pk_fma_f32 v[208:209], v[68:69], v[208:209], v[76:77]
	v_pk_fma_f32 v[210:211], v[70:71], v[210:211], v[78:79]
	v_pk_fma_f32 v[204:205], v[196:197], v[168:169], v[204:205] op_sel_hi:[0,1,1]
	v_pk_fma_f32 v[206:207], v[196:197], v[170:171], v[206:207] op_sel_hi:[0,1,1]
	v_pk_fma_f32 v[208:209], v[196:197], v[172:173], v[208:209] op_sel_hi:[0,1,1]
	v_pk_fma_f32 v[210:211], v[196:197], v[174:175], v[210:211] op_sel_hi:[0,1,1]
	v_pk_mul_f32 v[204:205], v[204:205], v[176:177]
	v_pk_mul_f32 v[206:207], v[206:207], v[178:179]
	v_pk_mul_f32 v[208:209], v[208:209], v[180:181]
	v_pk_mul_f32 v[210:211], v[210:211], v[182:183]
	v_cvt_pk_bf16_f32 v212, v204, v205
	v_cvt_pk_bf16_f32 v213, v206, v207
	v_cvt_pk_bf16_f32 v214, v208, v209
	v_cvt_pk_bf16_f32 v215, v210, v211
	global_store_dwordx4 v[100:101], v[212:215], off
	s_add_i32 s10, s10, s94
	s_cmp_lt_i32 s10, 0x8000
	s_cbranch_scc1 .Lrwp_loop
.Lrwp_done:
	s_waitcnt vmcnt(0)
.LBB0_2170:
	s_cmp_lt_i32 s87, 6
	s_cselect_b64 s[0:1], -1, 0
	s_xor_b64 s[2:3], s[66:67], -1
	s_or_b64 s[0:1], s[2:3], s[0:1]
	s_and_b64 vcc, exec, s[0:1]
	s_cbranch_vccnz .LBB0_2224
	s_waitcnt vmcnt(0)
	s_waitcnt vmcnt(0)
	s_barrier
	s_mov_b64 s[0:1], exec
	v_readlane_b32 s2, v251, 1
	v_readlane_b32 s3, v251, 2
	s_and_b64 s[2:3], s[0:1], s[2:3]
	s_mov_b64 exec, s[2:3]
	s_cbranch_execz .LBB0_2223
	s_add_i32 s2, 0, 0x23fc0
	v_mov_b32_e32 v0, s2
	s_waitcnt vmcnt(0) expcnt(0) lgkmcnt(0)
	ds_read_b32 v2, v0
	s_add_i32 s2, 0, 0x23fc4
	v_mov_b32_e32 v0, s2
	ds_read_b32 v0, v0
	s_waitcnt lgkmcnt(1)
	v_cmp_ne_u32_e32 vcc, 0, v2
	s_cbranch_vccnz .LBB0_2187
	v_readlane_b32 s2, v251, 0
	s_mul_i32 s16, s93, s2
	s_add_u32 s2, s96, 0x1000
	s_addc_u32 s3, s97, 0
	s_add_u32 s4, s96, 0x1100
	s_addc_u32 s5, s97, 0
	s_add_u32 s6, s96, 0x1200
	s_addc_u32 s7, s97, 0
	s_add_u32 s8, s96, 0x1300
	s_mul_i32 s16, s16, s92
	s_addc_u32 s9, s97, 0
	s_mov_b32 s17, 1
	v_mov_b32_e32 v16, 0
	s_branch .LBB0_2175
